# v12 + attn2: K-fragment ds_reads hoisted to step top, QK(next) MFMAs interleaved into the same wave's mask+max VALU stream (fast path when both blocks fully active)
# speedup vs baseline: 1.0141x; 1.0141x over previous
; #define MFMA32(a, b, c) __builtin_amdgcn_mfma_f32_32x32x16_bf16((a), (b), (c), 0, 0, 0)
; DI unsigned pk_bf16(float a, float b) { f32x2 v = {a, b}; bf2_t r = __builtin_convertvector(v, bf2_t); return __builtin_bit_cast(unsigned, r); }
;     ...
;         auto qk = [&](f32x16 (&s)[2], float& mi, int stg) {
;             const unsigned char* kb_ = lds + stg * STG + koff;
;             const unsigned mb = pk_bf16((m > -1e29f) ? -m : 0.f, 0.f) & 0xffffu;
;             mi = -__uint_as_float(mb << 16);
;             u32x4 qxw; qxw.x = hh ? 0u : mb; qxw.y = 0u; qxw.z = 0u; qxw.w = 0u;
;             u32x4 kxw; kxw.x = hh ? 0u : 0x3f80u; kxw.y = 0u; kxw.z = 0u; kxw.w = 0u;
;             const bf16x8 qx = __builtin_bit_cast(bf16x8, qxw), kx = __builtin_bit_cast(bf16x8, kxw);
;             f32x16 zero;
; #pragma unroll
;             for (int i = 0; i < 16; ++i) zero[i] = 0.f;
; #pragma unroll
;             for (int blk = 0; blk < 2; ++blk) {
;                 s[blk] = MFMA32(kx, qx, zero);
; #pragma unroll
;                 for (int ks = 0; ks < 4; ++ks) {
;                     const bf16x8 kf = *(const bf16x8*)(kb_ + blk * 4608 + ks * 32);
;                     s[blk] = MFMA32(kf, qf[ks], s[blk]);
;                 }
;             }
;         };
;     ...
;         auto stepf = [&](f32x16 (&s_cur)[2], const float mi_cur, f32x16 (&s_nxt)[2], float& mi_nxt, u32x4 (&rg_ld)[NJ], float& ck_ld, const u32x4 (&rg_st)[NJ], const float ck_st, int kk) {
;             const int kt = j0 + kk;
;             if (DEEP) { if (kk + 3 < ntl) gload(rg_ld, ck_ld, kt + 3); } else { if (kk + 2 < ntl) gload(rg_ld, ck_ld, kt + 2); }
;             if (MODE == 2 && kk + 2 < ntl) wnext2 = mrow[kt + 2];
;             if (kk + 1 < ntl && (kt + 1) * 64 <= qw0 + 31) qk(s_nxt, mi_nxt, (kk + 1) % 3);
.LBB0_3605:
	s_mul_hi_u32 s54, s41, 0xaaaaaaab
	s_lshr_b32 s54, s54, 1
	s_mul_i32 s54, s54, 0xd800
	v_subrev_u32_e32 v211, s54, v202
	v_add_u32_e32 v211, s48, v211
	ds_read_b128 v[212:215], v211
	ds_read_b128 v[216:219], v211 offset:32
	ds_read_b128 v[220:223], v211 offset:64
	ds_read_b128 v[224:227], v211 offset:96
	ds_read_b128 v[228:231], v211 offset:4608
	ds_read_b128 v[232:235], v211 offset:4640
	ds_read_b128 v[236:239], v211 offset:4672
	ds_read_b128 v[240:243], v211 offset:4704
	s_add_i32 s0, s45, -1
	s_cmp_lt_i32 s0, s40
	s_cselect_b64 s[6:7], -1, 0
	s_cmp_ge_i32 s0, s40
	s_cbranch_scc1 .LBB0_3607
	v_lshl_add_u64 v[4:5], s[42:43], 0, v[186:187]
	v_add_co_u32_e32 v4, vcc, 0x7350000, v4
	v_lshl_add_u64 v[6:7], s[42:43], 0, v[184:185]
	s_nop 0
	v_addc_co_u32_e32 v5, vcc, 0, v5, vcc
	v_add_co_u32_e32 v6, vcc, 0x15200000, v6
	s_nop 1
	v_addc_co_u32_e32 v7, vcc, 0, v7, vcc
	global_load_dwordx4 v[158:161], v[4:5], off offset:2048
	global_load_dwordx4 v[162:165], v[6:7], off offset:384

; #define MFMA32(a, b, c) __builtin_amdgcn_mfma_f32_32x32x16_bf16((a), (b), (c), 0, 0, 0)
; DI unsigned pk_bf16(float a, float b) { f32x2 v = {a, b}; bf2_t r = __builtin_convertvector(v, bf2_t); return __builtin_bit_cast(unsigned, r); }
;     ...
;         auto qk = [&](f32x16 (&s)[2], float& mi, int stg) {
;             const unsigned char* kb_ = lds + stg * STG + koff;
;             const unsigned mb = pk_bf16((m > -1e29f) ? -m : 0.f, 0.f) & 0xffffu;
;             mi = -__uint_as_float(mb << 16);
;             u32x4 qxw; qxw.x = hh ? 0u : mb; qxw.y = 0u; qxw.z = 0u; qxw.w = 0u;
;             u32x4 kxw; kxw.x = hh ? 0u : 0x3f80u; kxw.y = 0u; kxw.z = 0u; kxw.w = 0u;
;             const bf16x8 qx = __builtin_bit_cast(bf16x8, qxw), kx = __builtin_bit_cast(bf16x8, kxw);
;             f32x16 zero;
; #pragma unroll
;             for (int i = 0; i < 16; ++i) zero[i] = 0.f;
; #pragma unroll
;             for (int blk = 0; blk < 2; ++blk) {
;                 s[blk] = MFMA32(kx, qx, zero);
; #pragma unroll
;                 for (int ks = 0; ks < 4; ++ks) {
;                     const bf16x8 kf = *(const bf16x8*)(kb_ + blk * 4608 + ks * 32);
;                     s[blk] = MFMA32(kf, qf[ks], s[blk]);
;                 }
;             }
;         };
.LBB0_3609:
	s_mul_hi_u32 s0, s41, 0xaaaaaaab
	s_lshr_b32 s51, s0, 1
	s_add_i32 s52, s45, -3
	s_cmp_lt_i32 s52, s40
	s_cselect_b64 s[0:1], -1, 0
	s_add_i32 s4, s44, 33
	v_cmp_le_i32_e32 vcc, s4, v208
	s_mul_i32 s51, s51, 0xd800
	s_and_b64 s[0:1], s[0:1], vcc
	v_cmp_le_i32_e64 s[56:57], s44, v175
	s_and_b64 s[58:59], s[0:1], s[56:57]
	s_cmp_eq_u64 s[58:59], exec
	s_cbranch_scc1 .Lil1_fast
	s_and_saveexec_b64 s[26:27], s[0:1]
	s_cbranch_execz .LBB0_3611
	v_cmp_lt_f32_e64 s[4:5], s31, v183
	s_mov_b64 vcc, s[2:3]
	v_mov_b32_e32 v4, v3
	v_cndmask_b32_e64 v2, 0, -v183, s[4:5]
	v_cvt_pk_bf16_f32 v12, v2, 0
	v_cndmask_b32_sdwa v2, v3, v12, vcc dst_sel:DWORD dst_unused:UNUSED_PAD src0_sel:DWORD src1_sel:WORD_0
	v_mov_b32_e32 v5, v3
	v_lshlrev_b32_e32 v1, 16, v12
	v_xor_b32_e32 v188, 0x80000000, v1
	v_mfma_f32_32x32x16_bf16 v[66:81], v[130:133], v[2:5], 0
	s_waitcnt lgkmcnt(7)
	v_mfma_f32_32x32x16_bf16 v[50:65], v[212:215], v[142:145], v[66:81]
	s_waitcnt lgkmcnt(6)
	v_mfma_f32_32x32x16_bf16 v[50:65], v[216:219], v[146:149], v[50:65]
	s_waitcnt lgkmcnt(5)
	v_mfma_f32_32x32x16_bf16 v[50:65], v[220:223], v[150:153], v[50:65]
	s_waitcnt lgkmcnt(4)
	v_mfma_f32_32x32x16_bf16 v[50:65], v[224:227], v[154:157], v[50:65]
	s_waitcnt lgkmcnt(3)
	v_mfma_f32_32x32x16_bf16 v[66:81], v[228:231], v[142:145], v[66:81]
	s_waitcnt lgkmcnt(2)
	v_mfma_f32_32x32x16_bf16 v[66:81], v[232:235], v[146:149], v[66:81]
	s_waitcnt lgkmcnt(1)
	v_mfma_f32_32x32x16_bf16 v[66:81], v[236:239], v[150:153], v[66:81]
	s_waitcnt lgkmcnt(0)
	v_mfma_f32_32x32x16_bf16 v[66:81], v[240:243], v[154:157], v[66:81]

;     ...
;             if (__ballot(shift != 0.f) != 0) {
;                 if (__ballot(up) != 0) {
;                     const float alpha = __builtin_amdgcn_exp2f(m - mn);
;                     l *= alpha;
; #pragma unroll
;                     for (int db = 0; db < DVB; ++db)
; #pragma unroll
;                         for (int i = 0; i < 16; ++i) o[db][i] *= alpha;
;                     m = mn;
.Lil1_cont:
	v_cndmask_b32_e64 v34, 0, 1, s[4:5]
	v_cmp_ne_u32_e32 vcc, 0, v34
	s_cbranch_vccz .LBB0_3632
	v_sub_f32_e32 v34, v183, v189
	v_exp_f32_e32 v114, v34
	s_nop 0
	v_mul_f32_e32 v209, v173, v114
	v_pk_mul_f32 v[48:49], v[112:113], v[114:115] op_sel_hi:[1,0]
	v_pk_mul_f32 v[46:47], v[110:111], v[114:115] op_sel_hi:[1,0]
	v_pk_mul_f32 v[44:45], v[108:109], v[114:115] op_sel_hi:[1,0]
	v_pk_mul_f32 v[42:43], v[106:107], v[114:115] op_sel_hi:[1,0]
	v_pk_mul_f32 v[40:41], v[104:105], v[114:115] op_sel_hi:[1,0]
	v_pk_mul_f32 v[38:39], v[102:103], v[114:115] op_sel_hi:[1,0]
	v_pk_mul_f32 v[36:37], v[100:101], v[114:115] op_sel_hi:[1,0]
	v_pk_mul_f32 v[34:35], v[98:99], v[114:115] op_sel_hi:[1,0]
	v_pk_mul_f32 v[128:129], v[96:97], v[114:115] op_sel_hi:[1,0]
	v_pk_mul_f32 v[126:127], v[94:95], v[114:115] op_sel_hi:[1,0]
	v_pk_mul_f32 v[124:125], v[92:93], v[114:115] op_sel_hi:[1,0]
	v_pk_mul_f32 v[122:123], v[90:91], v[114:115] op_sel_hi:[1,0]
	v_pk_mul_f32 v[120:121], v[88:89], v[114:115] op_sel_hi:[1,0]
	v_pk_mul_f32 v[118:119], v[86:87], v[114:115] op_sel_hi:[1,0]
	v_pk_mul_f32 v[116:117], v[84:85], v[114:115] op_sel_hi:[1,0]
	v_pk_mul_f32 v[114:115], v[82:83], v[114:115] op_sel_hi:[1,0]
	s_cbranch_execnz .LBB0_3616

;     ...
;         auto stepf = [&](f32x16 (&s_cur)[2], const float mi_cur, f32x16 (&s_nxt)[2], float& mi_nxt, u32x4 (&rg_ld)[NJ], float& ck_ld, const u32x4 (&rg_st)[NJ], const float ck_st, int kk) {
;             const int kt = j0 + kk;
;             if (DEEP) { if (kk + 3 < ntl) gload(rg_ld, ck_ld, kt + 3); } else { if (kk + 2 < ntl) gload(rg_ld, ck_ld, kt + 2); }
;             if (MODE == 2 && kk + 2 < ntl) wnext2 = mrow[kt + 2];
;             if (kk + 1 < ntl && (kt + 1) * 64 <= qw0 + 31) qk(s_nxt, mi_nxt, (kk + 1) % 3);
;             if (kt * 64 <= qw0 + 31) softmax_pv(s_cur, mi_cur, kt, kk % 3);
;             if (MODE == 2) { wcur = wnext; wnext = wnext2; }
;             if (kk + 2 < ntl) lstore(rg_st, ck_st, (kk + 2) % 3);
;             __syncthreads();
.LBB0_3620:
	s_cmp_ge_i32 s52, s40
	s_waitcnt lgkmcnt(0)
	s_barrier
	s_cbranch_scc1 .LBB0_3631
	v_subrev_u32_e32 v211, s0, v204
	v_add_u32_e32 v211, s48, v211
	ds_read_b128 v[212:215], v211
	ds_read_b128 v[216:219], v211 offset:32
	ds_read_b128 v[220:223], v211 offset:64
	ds_read_b128 v[224:227], v211 offset:96
	ds_read_b128 v[228:231], v211 offset:4608
	ds_read_b128 v[232:235], v211 offset:4640
	ds_read_b128 v[236:239], v211 offset:4672
	ds_read_b128 v[240:243], v211 offset:4704
	s_cmp_ge_i32 s45, s40
	s_cbranch_scc1 .LBB0_3623
	v_lshl_add_u64 v[4:5], s[42:43], 0, v[186:187]
	v_add_co_u32_e32 v4, vcc, 0x73c0000, v4
	v_lshl_add_u64 v[6:7], s[42:43], 0, v[184:185]
	s_nop 0
	v_addc_co_u32_e32 v5, vcc, 0, v5, vcc
	v_add_co_u32_e32 v6, vcc, 0x15200000, v6
	s_nop 1
	v_addc_co_u32_e32 v7, vcc, 0, v7, vcc
	global_load_dwordx4 v[134:137], v[4:5], off offset:2048
	global_load_dwordx4 v[138:141], v[6:7], off offset:512
	s_waitcnt vmcnt(2)
	s_branch .Lmy_a2_w3join

; #define MFMA32(a, b, c) __builtin_amdgcn_mfma_f32_32x32x16_bf16((a), (b), (c), 0, 0, 0)
; DI unsigned pk_bf16(float a, float b) { f32x2 v = {a, b}; bf2_t r = __builtin_convertvector(v, bf2_t); return __builtin_bit_cast(unsigned, r); }
;     ...
;         auto qk = [&](f32x16 (&s)[2], float& mi, int stg) {
;             const unsigned char* kb_ = lds + stg * STG + koff;
;             const unsigned mb = pk_bf16((m > -1e29f) ? -m : 0.f, 0.f) & 0xffffu;
;             mi = -__uint_as_float(mb << 16);
;             u32x4 qxw; qxw.x = hh ? 0u : mb; qxw.y = 0u; qxw.z = 0u; qxw.w = 0u;
;             u32x4 kxw; kxw.x = hh ? 0u : 0x3f80u; kxw.y = 0u; kxw.z = 0u; kxw.w = 0u;
;             const bf16x8 qx = __builtin_bit_cast(bf16x8, qxw), kx = __builtin_bit_cast(bf16x8, kxw);
;             f32x16 zero;
; #pragma unroll
;             for (int i = 0; i < 16; ++i) zero[i] = 0.f;
; #pragma unroll
;             for (int blk = 0; blk < 2; ++blk) {
;                 s[blk] = MFMA32(kx, qx, zero);
; #pragma unroll
;                 for (int ks = 0; ks < 4; ++ks) {
;                     const bf16x8 kf = *(const bf16x8*)(kb_ + blk * 4608 + ks * 32);
;                     s[blk] = MFMA32(kf, qf[ks], s[blk]);
;                 }
;             }
;         };
;     ...
;             if (kk + 1 < ntl && (kt + 1) * 64 <= qw0 + 31) qk(s_nxt, mi_nxt, (kk + 1) % 3);
;             if (kt * 64 <= qw0 + 31) softmax_pv(s_cur, mi_cur, kt, kk % 3);
.LBB0_3625:
	s_cmp_lt_i32 s50, s40
	s_cselect_b64 s[6:7], -1, 0
	s_add_i32 s1, s44, 0x61
	v_cmp_le_i32_e32 vcc, s1, v208
	s_and_b64 s[6:7], s[6:7], vcc
	s_add_i32 s60, s44, 64
	v_cmp_le_i32_e64 s[56:57], s60, v175
	s_and_b64 s[58:59], s[6:7], s[56:57]
	s_cmp_eq_u64 s[58:59], exec
	s_cbranch_scc1 .Lil2_fast
	s_and_saveexec_b64 s[24:25], s[6:7]
	s_cbranch_execz .LBB0_3627
	v_cmp_lt_f32_e64 s[6:7], s31, v183
	s_mov_b64 vcc, s[2:3]
	v_mov_b32_e32 v4, v3
	v_cndmask_b32_e64 v2, 0, -v183, s[6:7]
	v_cvt_pk_bf16_f32 v12, v2, 0
	v_cndmask_b32_sdwa v2, v3, v12, vcc dst_sel:DWORD dst_unused:UNUSED_PAD src0_sel:DWORD src1_sel:WORD_0
	v_mov_b32_e32 v5, v3
	v_lshlrev_b32_e32 v1, 16, v12
	v_xor_b32_e32 v182, 0x80000000, v1
	v_mfma_f32_32x32x16_bf16 v[34:49], v[130:133], v[2:5], 0
	s_waitcnt lgkmcnt(7)
	v_mfma_f32_32x32x16_bf16 v[18:33], v[212:215], v[142:145], v[34:49]
	s_waitcnt lgkmcnt(6)
	v_mfma_f32_32x32x16_bf16 v[18:33], v[216:219], v[146:149], v[18:33]
	s_waitcnt lgkmcnt(5)
	v_mfma_f32_32x32x16_bf16 v[18:33], v[220:223], v[150:153], v[18:33]
	s_waitcnt lgkmcnt(4)
	v_mfma_f32_32x32x16_bf16 v[18:33], v[224:227], v[154:157], v[18:33]
	s_waitcnt lgkmcnt(3)
	v_mfma_f32_32x32x16_bf16 v[34:49], v[228:231], v[142:145], v[34:49]
	s_waitcnt lgkmcnt(2)
	v_mfma_f32_32x32x16_bf16 v[34:49], v[232:235], v[146:149], v[34:49]
	s_waitcnt lgkmcnt(1)
	v_mfma_f32_32x32x16_bf16 v[34:49], v[236:239], v[150:153], v[34:49]
	s_waitcnt lgkmcnt(0)
	v_mfma_f32_32x32x16_bf16 v[34:49], v[240:243], v[154:157], v[34:49]

;     ...
;             if (__ballot(shift != 0.f) != 0) {
;                 if (__ballot(up) != 0) {
;                     const float alpha = __builtin_amdgcn_exp2f(m - mn);
;                     l *= alpha;
; #pragma unroll
;                     for (int db = 0; db < DVB; ++db)
; #pragma unroll
;                         for (int i = 0; i < 16; ++i) o[db][i] *= alpha;
;                     m = mn;
;                 }
; #pragma unroll
;                 for (int blk = 0; blk < 2; ++blk)
; #pragma unroll
;                     for (int i = 0; i < 16; ++i) s[blk][i] -= shift;
;             }
.Lil2_cont:
	v_cndmask_b32_e64 v52, 0, 1, s[6:7]
	v_cmp_ne_u32_e32 vcc, 0, v52
	s_cbranch_vccz .LBB0_3633
	v_sub_f32_e32 v52, v183, v50
	v_exp_f32_e32 v52, v52
	s_nop 0
	v_mul_f32_e32 v173, v173, v52
	v_pk_mul_f32 v[112:113], v[112:113], v[52:53] op_sel_hi:[1,0]
	v_pk_mul_f32 v[110:111], v[110:111], v[52:53] op_sel_hi:[1,0]
	v_pk_mul_f32 v[108:109], v[108:109], v[52:53] op_sel_hi:[1,0]
	v_pk_mul_f32 v[106:107], v[106:107], v[52:53] op_sel_hi:[1,0]
	v_pk_mul_f32 v[104:105], v[104:105], v[52:53] op_sel_hi:[1,0]
	v_pk_mul_f32 v[102:103], v[102:103], v[52:53] op_sel_hi:[1,0]
	v_pk_mul_f32 v[100:101], v[100:101], v[52:53] op_sel_hi:[1,0]
	v_pk_mul_f32 v[98:99], v[98:99], v[52:53] op_sel_hi:[1,0]
	v_pk_mul_f32 v[96:97], v[96:97], v[52:53] op_sel_hi:[1,0]
	v_pk_mul_f32 v[94:95], v[94:95], v[52:53] op_sel_hi:[1,0]
	v_pk_mul_f32 v[92:93], v[92:93], v[52:53] op_sel_hi:[1,0]
	v_pk_mul_f32 v[90:91], v[90:91], v[52:53] op_sel_hi:[1,0]
	v_pk_mul_f32 v[88:89], v[88:89], v[52:53] op_sel_hi:[1,0]
	v_pk_mul_f32 v[86:87], v[86:87], v[52:53] op_sel_hi:[1,0]
	v_pk_mul_f32 v[84:85], v[84:85], v[52:53] op_sel_hi:[1,0]
	v_pk_mul_f32 v[82:83], v[82:83], v[52:53] op_sel_hi:[1,0]
	s_branch .LBB0_3634

;     ...
;         auto qk = [&](f32x16 (&s)[2], float& mi, int stg) {
;             const unsigned char* kb_ = lds + stg * STG + koff;
;             const unsigned mb = pk_bf16((m > -1e29f) ? -m : 0.f, 0.f) & 0xffffu;
;             mi = -__uint_as_float(mb << 16);
;             u32x4 qxw; qxw.x = hh ? 0u : mb; qxw.y = 0u; qxw.z = 0u; qxw.w = 0u;
;             u32x4 kxw; kxw.x = hh ? 0u : 0x3f80u; kxw.y = 0u; kxw.z = 0u; kxw.w = 0u;
;             const bf16x8 qx = __builtin_bit_cast(bf16x8, qxw), kx = __builtin_bit_cast(bf16x8, kxw);
;             f32x16 zero;
; #pragma unroll
;             for (int i = 0; i < 16; ++i) zero[i] = 0.f;
; #pragma unroll
;             for (int blk = 0; blk < 2; ++blk) {
;                 s[blk] = MFMA32(kx, qx, zero);
; #pragma unroll
;                 for (int ks = 0; ks < 4; ++ks) {
;                     const bf16x8 kf = *(const bf16x8*)(kb_ + blk * 4608 + ks * 32);
;                     s[blk] = MFMA32(kf, qf[ks], s[blk]);
;                 }
;             }
;         };
;         auto softmax_pv = [&](f32x16 (&s)[2], const float mi, int kt, int stg) {
;             const int k0 = kt * 64;
;             const unsigned char* sb = lds + stg * STG;
;             if (DRY != 1) {
;             if (MODE == 1) {
; #pragma unroll
;                 for (int blk = 0; blk < 2; ++blk)
; #pragma unroll
;                     for (int g = 0; g < 4; ++g) {
;                         const f32x4 c4 = *(const f32x4*)(sb + CK_OFF + (32 * blk + 8 * g + 4 * hh) * 4);
; #pragma unroll
;                         for (int e = 0; e < 4; ++e) s[blk][4 * g + e] -= c4[e];
;                     }
;             }
;             if (MODE == 2) {
;                 const u64 wsh = wcur >> (4 * hh);
;                 const int wlo = (int)(unsigned)wsh, whi = (int)(unsigned)(wsh >> 32);
; #pragma unroll
;                 for (int i = 0; i < 16; ++i) {
;                     const int bit = (i & 3) + 8 * (i >> 2);
;                     const unsigned m0 = (unsigned)__builtin_amdgcn_sbfe(wlo, bit, 1), m1 = (unsigned)__builtin_amdgcn_sbfe(whi, bit, 1);
;                     s[0][i] = __uint_as_float((__float_as_uint(s[0][i]) & m0) | (0xff800000u & ~m0));
;                     s[1][i] = __uint_as_float((__float_as_uint(s[1][i]) & m1) | (0xff800000u & ~m1));
;                 }
;             } else if (k0 + 63 > qw0) {
; #pragma unroll
.Lil1_fast:
	s_mov_b64 s[26:27], exec
	v_cmp_lt_f32_e64 s[4:5], s31, v183
	s_mov_b64 vcc, s[2:3]
	v_mov_b32_e32 v245, v3
	v_mov_b32_e32 v246, v3
	v_cndmask_b32_e64 v244, 0, -v183, s[4:5]
	v_cvt_pk_bf16_f32 v248, v244, 0
	v_cndmask_b32_sdwa v244, v3, v248, vcc dst_sel:DWORD dst_unused:UNUSED_PAD src0_sel:DWORD src1_sel:WORD_0
	v_mov_b32_e32 v247, v3
	v_lshlrev_b32_e32 v249, 16, v248
	v_xor_b32_e32 v188, 0x80000000, v249
	v_mfma_f32_32x32x16_bf16 v[66:81], v[130:133], v[244:247], 0
	v_lshrrev_b64 v[6:7], v170, v[116:117]
	v_bfe_i32 v1, v6, 0, 1
	v_bitop3_b32 v18, v18, s34, v1 bitop3:0xe4
	v_bfe_i32 v1, v6, 1, 1
	v_bfe_i32 v4, v7, 1, 1
	v_bfe_i32 v2, v7, 0, 1
	v_bitop3_b32 v19, v19, s34, v1 bitop3:0xe4
	v_bitop3_b32 v1, v35, s34, v4 bitop3:0xe4
	v_bfe_i32 v4, v6, 2, 1
	v_bfe_i32 v5, v7, 2, 1
	v_bitop3_b32 v2, v34, s34, v2 bitop3:0xe4
	s_waitcnt lgkmcnt(7)
	v_mfma_f32_32x32x16_bf16 v[50:65], v[212:215], v[142:145], v[66:81]
	v_bitop3_b32 v20, v20, s34, v4 bitop3:0xe4
	v_bitop3_b32 v4, v36, s34, v5 bitop3:0xe4
	v_bfe_i32 v5, v6, 3, 1
	v_bfe_i32 v8, v7, 3, 1
	v_bfe_i32 v10, v6, 11, 1
	v_bfe_i32 v34, v6, 18, 1
	v_bfe_i32 v35, v7, 18, 1
	v_bitop3_b32 v21, v21, s34, v5 bitop3:0xe4
	v_bitop3_b32 v17, v37, s34, v8 bitop3:0xe4
	v_bfe_i32 v5, v6, 8, 1
	s_waitcnt lgkmcnt(6)
	v_mfma_f32_32x32x16_bf16 v[50:65], v[216:219], v[146:149], v[50:65]
	v_bfe_i32 v8, v7, 8, 1
	v_bitop3_b32 v25, v25, s34, v10 bitop3:0xe4
	v_bitop3_b32 v28, v28, s34, v34 bitop3:0xe4
	v_bitop3_b32 v10, v44, s34, v35 bitop3:0xe4
	v_max_f32_e32 v34, v19, v19
	v_max_f32_e32 v35, v18, v18
	v_bitop3_b32 v22, v22, s34, v5 bitop3:0xe4
	v_bitop3_b32 v16, v38, s34, v8 bitop3:0xe4
	v_bfe_i32 v5, v6, 9, 1
	v_bfe_i32 v8, v7, 9, 1
	v_max_f32_e32 v34, v35, v34
	s_waitcnt lgkmcnt(5)
	v_mfma_f32_32x32x16_bf16 v[50:65], v[220:223], v[150:153], v[50:65]
	v_bitop3_b32 v23, v23, s34, v5 bitop3:0xe4
	v_bitop3_b32 v5, v39, s34, v8 bitop3:0xe4
	v_bfe_i32 v8, v6, 10, 1
	v_max3_f32 v34, v34, v20, v21
	v_bfe_i32 v12, v6, 16, 1
	v_bfe_i32 v14, v6, 17, 1
	v_bitop3_b32 v24, v24, s34, v8 bitop3:0xe4
	v_max3_f32 v34, v34, v22, v23
	v_bfe_i32 v36, v6, 19, 1
	v_bitop3_b32 v26, v26, s34, v12 bitop3:0xe4
	v_bitop3_b32 v27, v27, s34, v14 bitop3:0xe4
	s_waitcnt lgkmcnt(4)
	v_mfma_f32_32x32x16_bf16 v[50:65], v[224:227], v[154:157], v[50:65]
	v_max3_f32 v34, v34, v24, v25
	v_bfe_i32 v38, v6, 24, 1
	v_bfe_i32 v114, v6, 25, 1
	v_bitop3_b32 v29, v29, s34, v36 bitop3:0xe4
	v_max3_f32 v34, v34, v26, v27
	v_bfe_i32 v116, v6, 26, 1
	v_bfe_i32 v118, v6, 27, 1
	v_bitop3_b32 v30, v30, s34, v38 bitop3:0xe4
	v_bitop3_b32 v31, v31, s34, v114 bitop3:0xe4
	v_max3_f32 v34, v34, v28, v29
	s_waitcnt lgkmcnt(3)
	v_mfma_f32_32x32x16_bf16 v[66:81], v[228:231], v[142:145], v[66:81]
	v_bitop3_b32 v32, v32, s34, v116 bitop3:0xe4
	v_bitop3_b32 v33, v33, s34, v118 bitop3:0xe4
	v_max3_f32 v34, v34, v30, v31
	v_max3_f32 v34, v34, v32, v33
	v_max3_f32 v34, v34, v2, v1
	v_bfe_i32 v9, v7, 10, 1
	v_bfe_i32 v11, v7, 11, 1
	v_max3_f32 v34, v34, v4, v17
	v_bfe_i32 v13, v7, 16, 1
	v_bfe_i32 v15, v7, 17, 1
	v_bfe_i32 v37, v7, 19, 1
	s_waitcnt lgkmcnt(2)
	v_mfma_f32_32x32x16_bf16 v[66:81], v[232:235], v[146:149], v[66:81]
	v_bfe_i32 v39, v7, 24, 1
	v_bfe_i32 v115, v7, 25, 1
	v_bfe_i32 v117, v7, 26, 1
	v_bfe_i32 v119, v7, 27, 1
	v_bitop3_b32 v6, v40, s34, v9 bitop3:0xe4
	v_bitop3_b32 v7, v41, s34, v11 bitop3:0xe4
	v_max3_f32 v34, v34, v16, v5
	v_bitop3_b32 v8, v42, s34, v13 bitop3:0xe4
	v_bitop3_b32 v9, v43, s34, v15 bitop3:0xe4
	v_max3_f32 v34, v34, v6, v7
	v_bitop3_b32 v11, v45, s34, v37 bitop3:0xe4
	s_waitcnt lgkmcnt(1)
	v_mfma_f32_32x32x16_bf16 v[66:81], v[236:239], v[150:153], v[66:81]
	v_max3_f32 v34, v34, v8, v9
	v_bitop3_b32 v12, v46, s34, v39 bitop3:0xe4
	v_bitop3_b32 v13, v47, s34, v115 bitop3:0xe4
	v_max3_f32 v34, v34, v10, v11
	v_bitop3_b32 v14, v48, s34, v117 bitop3:0xe4
	v_bitop3_b32 v15, v49, s34, v119 bitop3:0xe4
	v_max3_f32 v34, v34, v12, v13
	v_max3_f32 v34, v34, v14, v15
	v_mov_b32_e32 v35, v34
	s_nop 1
	s_waitcnt lgkmcnt(0)
	v_mfma_f32_32x32x16_bf16 v[66:81], v[240:243], v[154:157], v[66:81]
	v_permlane32_swap_b32_e32 v34, v35
	v_max_f32_e32 v35, v35, v35
	v_max_f32_e32 v34, v34, v34
	v_max_f32_e32 v176, v34, v35
	v_pk_add_f32 v[34:35], v[182:183], v[176:177]
	s_nop 0
	v_cvt_pk_bf16_f32 v36, v34, 0
	v_lshlrev_b32_e32 v36, 16, v36
	v_cmp_gt_f32_e64 s[4:5], v34, v35
	s_nop 1
	v_cndmask_b32_e64 v189, v183, v36, s[4:5]
	v_sub_f32_e32 v176, v189, v182
	v_cmp_neq_f32_e32 vcc, 0, v176
	s_cbranch_vccz .LBB0_3617
	s_branch .Lil1_cont
;     ...
;         auto qk = [&](f32x16 (&s)[2], float& mi, int stg) {
;             const unsigned char* kb_ = lds + stg * STG + koff;
;             const unsigned mb = pk_bf16((m > -1e29f) ? -m : 0.f, 0.f) & 0xffffu;
;             mi = -__uint_as_float(mb << 16);
;             u32x4 qxw; qxw.x = hh ? 0u : mb; qxw.y = 0u; qxw.z = 0u; qxw.w = 0u;
;             u32x4 kxw; kxw.x = hh ? 0u : 0x3f80u; kxw.y = 0u; kxw.z = 0u; kxw.w = 0u;
;             const bf16x8 qx = __builtin_bit_cast(bf16x8, qxw), kx = __builtin_bit_cast(bf16x8, kxw);
;             f32x16 zero;
; #pragma unroll
;             for (int i = 0; i < 16; ++i) zero[i] = 0.f;
; #pragma unroll
;             for (int blk = 0; blk < 2; ++blk) {
;                 s[blk] = MFMA32(kx, qx, zero);
; #pragma unroll
;                 for (int ks = 0; ks < 4; ++ks) {
;                     const bf16x8 kf = *(const bf16x8*)(kb_ + blk * 4608 + ks * 32);
;                     s[blk] = MFMA32(kf, qf[ks], s[blk]);
;                 }
;             }
;         };
;         auto softmax_pv = [&](f32x16 (&s)[2], const float mi, int kt, int stg) {
;             const int k0 = kt * 64;
;             const unsigned char* sb = lds + stg * STG;
;             if (DRY != 1) {
;             if (MODE == 1) {
; #pragma unroll
;                 for (int blk = 0; blk < 2; ++blk)
; #pragma unroll
;                     for (int g = 0; g < 4; ++g) {
;                         const f32x4 c4 = *(const f32x4*)(sb + CK_OFF + (32 * blk + 8 * g + 4 * hh) * 4);
; #pragma unroll
;                         for (int e = 0; e < 4; ++e) s[blk][4 * g + e] -= c4[e];
;                     }
;             }
;             if (MODE == 2) {
;                 const u64 wsh = wcur >> (4 * hh);
;                 const int wlo = (int)(unsigned)wsh, whi = (int)(unsigned)(wsh >> 32);
; #pragma unroll
;                 for (int i = 0; i < 16; ++i) {
;                     const int bit = (i & 3) + 8 * (i >> 2);
;                     const unsigned m0 = (unsigned)__builtin_amdgcn_sbfe(wlo, bit, 1), m1 = (unsigned)__builtin_amdgcn_sbfe(whi, bit, 1);
;                     s[0][i] = __uint_as_float((__float_as_uint(s[0][i]) & m0) | (0xff800000u & ~m0));
;                     s[1][i] = __uint_as_float((__float_as_uint(s[1][i]) & m1) | (0xff800000u & ~m1));
;                 }
;             } else if (k0 + 63 > qw0) {
; #pragma unroll
.Lil2_fast:
	s_mov_b64 s[24:25], exec
	s_add_i32 s0, s44, 64
	v_cmp_lt_f32_e64 s[6:7], s31, v183
	s_mov_b64 vcc, s[2:3]
	v_mov_b32_e32 v245, v3
	v_mov_b32_e32 v246, v3
	v_cndmask_b32_e64 v244, 0, -v183, s[6:7]
	v_cvt_pk_bf16_f32 v248, v244, 0
	v_cndmask_b32_sdwa v244, v3, v248, vcc dst_sel:DWORD dst_unused:UNUSED_PAD src0_sel:DWORD src1_sel:WORD_0
	v_mov_b32_e32 v247, v3
	v_lshlrev_b32_e32 v249, 16, v248
	v_xor_b32_e32 v182, 0x80000000, v249
	v_mfma_f32_32x32x16_bf16 v[34:49], v[130:133], v[244:247], 0
	v_lshrrev_b64 v[6:7], v170, v[192:193]
	v_bfe_i32 v10, v6, 3, 1
	v_bfe_i32 v1, v6, 0, 1
	v_bitop3_b32 v17, v53, s34, v10 bitop3:0xe4
	v_bfe_i32 v10, v6, 8, 1
	v_bitop3_b32 v2, v50, s34, v1 bitop3:0xe4
	v_bfe_i32 v1, v6, 1, 1
	v_bitop3_b32 v16, v54, s34, v10 bitop3:0xe4
	v_bfe_i32 v10, v6, 9, 1
	v_bfe_i32 v8, v7, 1, 1
	v_bitop3_b32 v1, v51, s34, v1 bitop3:0xe4
	s_waitcnt lgkmcnt(7)
	v_mfma_f32_32x32x16_bf16 v[18:33], v[212:215], v[142:145], v[34:49]
	v_bfe_i32 v9, v7, 2, 1
	v_bitop3_b32 v55, v55, s34, v10 bitop3:0xe4
	v_bfe_i32 v10, v6, 10, 1
	v_bfe_i32 v50, v7, 16, 1
	v_bfe_i32 v51, v7, 17, 1
	v_bfe_i32 v4, v6, 2, 1
	v_bitop3_b32 v56, v56, s34, v10 bitop3:0xe4
	v_bfe_i32 v10, v6, 11, 1
	v_bitop3_b32 v67, v67, s34, v8 bitop3:0xe4
	v_bitop3_b32 v68, v68, s34, v9 bitop3:0xe4
	v_bitop3_b32 v8, v74, s34, v50 bitop3:0xe4
	s_waitcnt lgkmcnt(6)
	v_mfma_f32_32x32x16_bf16 v[18:33], v[216:219], v[146:149], v[18:33]
	v_bitop3_b32 v9, v75, s34, v51 bitop3:0xe4
	v_max_f32_e32 v50, v1, v1
	v_max_f32_e32 v51, v2, v2
	v_bitop3_b32 v4, v52, s34, v4 bitop3:0xe4
	v_bitop3_b32 v57, v57, s34, v10 bitop3:0xe4
	v_bfe_i32 v10, v6, 16, 1
	v_max_f32_e32 v50, v51, v50
	v_bitop3_b32 v58, v58, s34, v10 bitop3:0xe4
	v_bfe_i32 v10, v6, 17, 1
	v_max3_f32 v50, v50, v4, v17
	s_waitcnt lgkmcnt(5)
	v_mfma_f32_32x32x16_bf16 v[18:33], v[220:223], v[150:153], v[18:33]
	v_bitop3_b32 v59, v59, s34, v10 bitop3:0xe4
	v_bfe_i32 v10, v6, 18, 1
	v_max3_f32 v50, v50, v16, v55
	v_bitop3_b32 v60, v60, s34, v10 bitop3:0xe4
	v_bfe_i32 v10, v6, 19, 1
	v_max3_f32 v50, v50, v56, v57
	v_bfe_i32 v54, v6, 24, 1
	v_bfe_i32 v117, v6, 25, 1
	v_bitop3_b32 v61, v61, s34, v10 bitop3:0xe4
	v_max3_f32 v50, v50, v58, v59
	v_bfe_i32 v119, v6, 26, 1
	s_waitcnt lgkmcnt(4)
	v_mfma_f32_32x32x16_bf16 v[18:33], v[224:227], v[154:157], v[18:33]
	v_bfe_i32 v6, v6, 27, 1
	v_bitop3_b32 v62, v62, s34, v54 bitop3:0xe4
	v_bitop3_b32 v63, v63, s34, v117 bitop3:0xe4
	v_max3_f32 v50, v50, v60, v61
	v_bfe_i32 v5, v7, 0, 1
	v_bitop3_b32 v64, v64, s34, v119 bitop3:0xe4
	v_bitop3_b32 v65, v65, s34, v6 bitop3:0xe4
	v_max3_f32 v50, v50, v62, v63
	v_bfe_i32 v11, v7, 3, 1
	v_bitop3_b32 v66, v66, s34, v5 bitop3:0xe4
	v_max3_f32 v50, v50, v64, v65
	s_waitcnt lgkmcnt(3)
	v_mfma_f32_32x32x16_bf16 v[34:49], v[228:231], v[142:145], v[34:49]
	v_bfe_i32 v12, v7, 8, 1
	v_bfe_i32 v13, v7, 9, 1
	v_bitop3_b32 v69, v69, s34, v11 bitop3:0xe4
	v_max3_f32 v50, v50, v66, v67
	v_bfe_i32 v14, v7, 10, 1
	v_bfe_i32 v15, v7, 11, 1
	v_bitop3_b32 v70, v70, s34, v12 bitop3:0xe4
	v_bitop3_b32 v5, v71, s34, v13 bitop3:0xe4
	v_max3_f32 v50, v50, v68, v69
	v_bfe_i32 v52, v7, 18, 1
	v_bfe_i32 v53, v7, 19, 1
	s_waitcnt lgkmcnt(2)
	v_mfma_f32_32x32x16_bf16 v[34:49], v[232:235], v[146:149], v[34:49]
	v_bfe_i32 v116, v7, 24, 1
	v_bfe_i32 v118, v7, 25, 1
	v_bfe_i32 v120, v7, 26, 1
	v_bfe_i32 v121, v7, 27, 1
	v_bitop3_b32 v6, v72, s34, v14 bitop3:0xe4
	v_bitop3_b32 v7, v73, s34, v15 bitop3:0xe4
	v_max3_f32 v50, v50, v70, v5
	v_max3_f32 v50, v50, v6, v7
	v_bitop3_b32 v10, v76, s34, v52 bitop3:0xe4
	v_bitop3_b32 v11, v77, s34, v53 bitop3:0xe4
	s_waitcnt lgkmcnt(1)
	v_mfma_f32_32x32x16_bf16 v[34:49], v[236:239], v[150:153], v[34:49]
	v_max3_f32 v50, v50, v8, v9
	v_bitop3_b32 v12, v78, s34, v116 bitop3:0xe4
	v_bitop3_b32 v13, v79, s34, v118 bitop3:0xe4
	v_max3_f32 v50, v50, v10, v11
	v_bitop3_b32 v14, v80, s34, v120 bitop3:0xe4
	v_bitop3_b32 v15, v81, s34, v121 bitop3:0xe4
	v_max3_f32 v50, v50, v12, v13
	v_max3_f32 v50, v50, v14, v15
	v_mov_b32_e32 v51, v50
	s_nop 1
	v_permlane32_swap_b32_e32 v50, v51
	s_waitcnt lgkmcnt(0)
	v_mfma_f32_32x32x16_bf16 v[34:49], v[240:243], v[154:157], v[34:49]
	v_max_f32_e32 v51, v51, v51
	v_max_f32_e32 v50, v50, v50
	v_max_f32_e32 v176, v50, v51
	v_mov_b32_e32 v189, v183
	v_pk_add_f32 v[50:51], v[188:189], v[176:177]
	s_nop 0
	v_cvt_pk_bf16_f32 v52, v50, 0
	v_lshlrev_b32_e32 v52, 16, v52
	v_cmp_gt_f32_e64 s[6:7], v50, v51
	s_nop 1
	v_cndmask_b32_e64 v50, v183, v52, s[6:7]
	v_sub_f32_e32 v51, v50, v188
	v_cmp_neq_f32_e32 vcc, 0, v51
	s_cbranch_vccz .LBB0_3635
	s_branch .Lil2_cont
